# k17 plus: static s_setprio 1 for waves 0-3 (older half) across the MLA attention loop
# speedup vs baseline: 1.0030x; 1.0012x over previous
; __device__ __forceinline__ void attn_mla_phase(LAS unsigned char* lds, const bf16_t* QB, const bf16_t* KV, const bf16_t* KRR, bf16_t* O, int G, int bx) {
;     ...
;     const int nslots = xs ? G / 8 : G, slot = xs ? bx / 8 : bx, xcd = xs ? bx % 8 : 0, npx = xs ? 16 : 128;
;     const int nent = npx * 40;
;     const int skey = tid >> 3, sch = tid & 7, rkey = tid >> 2, rch = tid & 3;
;     const int kdst = skey * 208 + sch * 16, rdst = rkey * 208 + 128 + rch * 16, vdst = (sch >> 2) * 4096 + skey * 64 + (sch & 3) * 16;
;     const unsigned trb = (unsigned)(size_t)(lds + VOFF) + (unsigned)((4 * hi + ((lane & 15) >> 2)) * 64 + 32 * ((lane >> 4) & 1) + 8 * (lane & 3));
.LBB0_763:
	s_or_b64 exec, exec, s[20:21]
	s_add_u32 s36, s18, 0xde00000
	v_lshlrev_b32_e32 v0, 2, v20
	v_lshrrev_b32_e32 v3, 2, v14
	s_addc_u32 s37, s19, 0
	s_ashr_i32 s2, s1, 3
	v_and_or_b32 v3, v3, 3, v0
	v_lshlrev_b32_e32 v5, 1, v14
	v_lshlrev_b32_e32 v6, 3, v14
	s_and_b64 s[8:9], s[12:13], exec
	v_lshlrev_b32_e32 v3, 6, v3
	v_and_b32_e32 v5, 32, v5
	v_and_b32_e32 v6, 24, v6
	s_cselect_b32 s20, s2, s1
	v_or3_b32 v5, v3, v5, v6
	v_readlane_b32 s1, v254, 63
	v_lshlrev_b32_e32 v2, 3, v22
	v_lshlrev_b32_e32 v2, 1, v2
	v_add_u32_e32 v201, s1, v5
	v_readlane_b32 s1, v255, 0
	v_mov_b32_e32 v3, v19
	v_lshlrev_b32_e32 v1, 3, v20
	v_add_u32_e32 v202, s1, v5
	v_readlane_b32 s1, v255, 1
	v_lshlrev_b32_e32 v4, 3, v21
	v_lshl_add_u64 v[164:165], s[16:17], 0, v[2:3]
	v_add_u32_e32 v203, s1, v5
	v_readlane_b32 s1, v255, 2
	v_mad_u32_u24 v2, v15, s10, 0
	v_add_u32_e32 v3, v9, v18
	v_add_u32_e32 v204, s1, v5
	v_readlane_b32 s1, v255, 3
	v_mov_b32_e32 v104, v19
	v_mov_b32_e32 v105, v19
	v_add_u32_e32 v205, s1, v5
	v_readlane_b32 s1, v255, 4
	v_mov_b32_e32 v106, v19
	v_mov_b32_e32 v107, v19
	v_add_u32_e32 v206, s1, v5
	v_readlane_b32 s1, v255, 5
	v_lshlrev_b32_e32 v18, 1, v4
	v_lshlrev_b32_e32 v166, 1, v1
	v_add_u32_e32 v207, s1, v5
	v_readlane_b32 s1, v255, 6
	v_lshlrev_b32_e32 v168, 1, v0
	v_add_u32_e32 v234, v2, v8
	v_add_u32_e32 v208, s1, v5
	v_readlane_b32 s1, v255, 7
	v_add_u32_e32 v235, 0, v3
	s_waitcnt lgkmcnt(0)
	v_add_u32_e32 v209, s1, v5
	v_readlane_b32 s1, v255, 8
	s_barrier
	s_nop 0
	v_add_u32_e32 v210, s1, v5
	v_readlane_b32 s1, v255, 9
	s_nop 1
	v_add_u32_e32 v211, s1, v5
	v_readlane_b32 s1, v255, 10
	s_nop 1
	v_add_u32_e32 v212, s1, v5
	s_add_i32 s1, 0, 0x8000
	v_add_u32_e32 v213, s1, v5
	v_readlane_b32 s1, v255, 11
	s_nop 1
	v_add_u32_e32 v214, s1, v5
	v_readlane_b32 s1, v255, 12
	s_nop 1
	v_add_u32_e32 v215, s1, v5
	v_readlane_b32 s1, v255, 13
	s_nop 1
	v_add_u32_e32 v217, s1, v5
	v_readlane_b32 s1, v254, 50
	s_nop 1
	v_add_u32_e32 v218, s1, v5
	v_readlane_b32 s1, v255, 14
	s_nop 1
	v_add_u32_e32 v219, s1, v5
	v_readlane_b32 s1, v255, 15
	s_nop 1
	v_add_u32_e32 v220, s1, v5
	v_readlane_b32 s1, v255, 16
	s_nop 1
	v_add_u32_e32 v221, s1, v5
	v_readlane_b32 s1, v255, 17
	s_nop 1
	v_add_u32_e32 v222, s1, v5
	v_readlane_b32 s1, v255, 18
	s_nop 1
	v_add_u32_e32 v223, s1, v5
	v_readlane_b32 s1, v255, 19
	s_nop 1
	v_add_u32_e32 v224, s1, v5
	v_readlane_b32 s1, v255, 20
	s_nop 1
	v_add_u32_e32 v225, s1, v5
	v_readlane_b32 s1, v255, 21
	s_nop 1
	v_add_u32_e32 v226, s1, v5
	v_readlane_b32 s1, v255, 22
	s_nop 1
	v_add_u32_e32 v227, s1, v5
	v_readlane_b32 s1, v255, 23
	s_nop 1
	v_add_u32_e32 v228, s1, v5
	v_readlane_b32 s1, v255, 24
	s_nop 1
	v_add_u32_e32 v229, s1, v5
	s_add_i32 s1, 0, 0xa000
	v_add_u32_e32 v230, s1, v5
	v_readlane_b32 s1, v255, 25
	s_nop 1
	v_add_u32_e32 v231, s1, v5
	v_readlane_b32 s1, v255, 26
	s_nop 1
	v_add_u32_e32 v232, s1, v5
	v_readlane_b32 s1, v255, 27
	s_nop 1
	v_add_u32_e32 v233, s1, v5
	s_cmp_eq_u64 s[40:41], 0
	s_cbranch_scc1 .Lmla_prio_in
	s_setprio 1
